# in-proj epilogue pass-through tiles: eight accumulator copies per row block removed (convert straight from the accumulators)
# baseline (speedup 1.0000x reference)
.LBB0_179:
	v_cvt_pk_bf16_f32 v124, v124, v125
	v_cvt_pk_bf16_f32 v125, v126, v127
	v_cvt_pk_bf16_f32 v126, v120, v121
	v_cvt_pk_bf16_f32 v127, v122, v123
	s_branch .Lp1pl_15
.LBB0_180:
	v_cvt_pk_bf16_f32 v124, v166, v167
	v_cvt_pk_bf16_f32 v125, v168, v169
	v_cvt_pk_bf16_f32 v126, v170, v171
	v_cvt_pk_bf16_f32 v127, v172, v173
.Lp1pl_15:
	s_ashr_i32 s29, s28, 31
	s_lshl_b64 s[28:29], s[28:29], 1
	s_add_u32 s96, s30, s28
	s_addc_u32 s97, s31, s29
	v_add_u32_e32 v202, s24, v138
	v_mul_u32_u24_e32 v202, s26, v202
	v_lshl_add_u32 v202, v202, 1, v136
	s_cmp_gt_i32 s13, 2
	s_mov_b64 s[28:29], -1
	global_store_dwordx4 v202, v[124:127], s[96:97] nt
	s_cbranch_scc0 .LBB0_182
	s_nop 0
	v_mul_f32_e32 v124, 0xbfb8aa3b, v116
	v_mul_f32_e32 v125, 0xbfb8aa3b, v117
	v_mul_f32_e32 v126, 0xbfb8aa3b, v118
	v_mul_f32_e32 v127, 0xbfb8aa3b, v119
	v_mul_f32_e32 v166, 0xbfb8aa3b, v112
	v_mul_f32_e32 v167, 0xbfb8aa3b, v113
	v_mul_f32_e32 v168, 0xbfb8aa3b, v114
	v_mul_f32_e32 v169, 0xbfb8aa3b, v115
	v_exp_f32_e32 v124, v124
	v_exp_f32_e32 v125, v125
	v_exp_f32_e32 v126, v126
	v_exp_f32_e32 v127, v127
	v_exp_f32_e32 v166, v166
	v_exp_f32_e32 v167, v167
	v_exp_f32_e32 v168, v168
	v_exp_f32_e32 v169, v169
	v_add_f32_e32 v124, 1.0, v124
	v_add_f32_e32 v125, 1.0, v125
	v_add_f32_e32 v126, 1.0, v126
	v_add_f32_e32 v127, 1.0, v127
	v_add_f32_e32 v166, 1.0, v166
	v_add_f32_e32 v167, 1.0, v167
	v_add_f32_e32 v168, 1.0, v168
	v_add_f32_e32 v169, 1.0, v169
	v_rcp_f32_e32 v124, v124
	v_rcp_f32_e32 v125, v125
	v_rcp_f32_e32 v126, v126
	v_rcp_f32_e32 v127, v127
	v_rcp_f32_e32 v166, v166
	v_rcp_f32_e32 v167, v167
	v_rcp_f32_e32 v168, v168
	v_rcp_f32_e32 v169, v169
	s_mov_b64 s[28:29], 0

.LBB0_185:
	v_cvt_pk_bf16_f32 v115, v114, v115
	v_cvt_pk_bf16_f32 v114, v112, v113
	v_cvt_pk_bf16_f32 v112, v116, v117
	v_cvt_pk_bf16_f32 v113, v118, v119
	s_branch .Lp1pl_14

.Lp1pl_14:
	global_store_dwordx4 v202, v[112:115], s[96:97] offset:256 nt
	s_cmp_gt_i32 s13, 2
	s_mov_b64 s[28:29], -1
	s_cbranch_scc0 .LBB0_188
	v_mul_f32_e32 v112, 0xbfb8aa3b, v108
	v_exp_f32_e32 v112, v112
	v_mul_f32_e32 v113, 0xbfb8aa3b, v109
	v_exp_f32_e32 v113, v113
	v_mul_f32_e32 v115, 0xbfb8aa3b, v111
	v_add_f32_e32 v112, 1.0, v112
	v_rcp_f32_e32 v114, v112
	v_mul_f32_e32 v112, 0xbfb8aa3b, v110
	v_exp_f32_e32 v112, v112
	v_exp_f32_e32 v117, v115
	v_add_f32_e32 v113, 1.0, v113
	v_rcp_f32_e32 v115, v113
	v_add_f32_e32 v112, 1.0, v112
	v_mul_f32_e32 v113, 0xbfb8aa3b, v104
	v_rcp_f32_e32 v116, v112
	v_add_f32_e32 v112, 1.0, v117
	v_exp_f32_e32 v113, v113
	v_mul_f32_e32 v117, 0xbfb8aa3b, v105
	v_exp_f32_e32 v119, v117
	v_rcp_f32_e32 v117, v112
	v_add_f32_e32 v112, 1.0, v113
	v_mul_f32_e32 v113, 0xbfb8aa3b, v106
	v_rcp_f32_e32 v118, v112
	v_add_f32_e32 v112, 1.0, v119
	v_exp_f32_e32 v113, v113
	v_mul_f32_e32 v119, 0xbfb8aa3b, v107
	v_exp_f32_e32 v123, v119
	v_rcp_f32_e32 v119, v112
	v_add_f32_e32 v112, 1.0, v113
	v_rcp_f32_e32 v122, v112
	v_add_f32_e32 v112, 1.0, v123
	v_rcp_f32_e32 v123, v112
	s_mov_b64 s[28:29], 0

.LBB0_191:
	v_cvt_pk_bf16_f32 v203, v106, v107
	v_cvt_pk_bf16_f32 v106, v108, v109
	v_cvt_pk_bf16_f32 v107, v110, v111
	v_cvt_pk_bf16_f32 v108, v104, v105
	v_mov_b32_e32 v109, v203
	s_branch .Lp1pl_13
.LBB0_192:
	v_cvt_pk_bf16_f32 v106, v114, v115
	v_cvt_pk_bf16_f32 v107, v116, v117
	v_cvt_pk_bf16_f32 v108, v118, v119
	v_cvt_pk_bf16_f32 v109, v122, v123
.Lp1pl_13:
	s_mul_i32 s94, s26, 0x20
	s_add_u32 s94, s96, s94
	s_addc_u32 s95, s97, 0
	s_cmp_gt_i32 s13, 2
	s_mov_b64 s[28:29], -1
	global_store_dwordx4 v202, v[106:109], s[94:95] nt
	s_cbranch_scc0 .LBB0_194
	s_nop 0
	v_mul_f32_e32 v106, 0xbfb8aa3b, v100
	v_mul_f32_e32 v107, 0xbfb8aa3b, v101
	v_mul_f32_e32 v108, 0xbfb8aa3b, v102
	v_mul_f32_e32 v109, 0xbfb8aa3b, v103
	v_mul_f32_e32 v110, 0xbfb8aa3b, v96
	v_mul_f32_e32 v111, 0xbfb8aa3b, v97
	v_mul_f32_e32 v114, 0xbfb8aa3b, v98
	v_mul_f32_e32 v115, 0xbfb8aa3b, v99
	v_exp_f32_e32 v106, v106
	v_exp_f32_e32 v107, v107
	v_exp_f32_e32 v108, v108
	v_exp_f32_e32 v109, v109
	v_exp_f32_e32 v110, v110
	v_exp_f32_e32 v111, v111
	v_exp_f32_e32 v114, v114
	v_exp_f32_e32 v115, v115
	v_add_f32_e32 v106, 1.0, v106
	v_add_f32_e32 v107, 1.0, v107
	v_add_f32_e32 v108, 1.0, v108
	v_add_f32_e32 v109, 1.0, v109
	v_add_f32_e32 v110, 1.0, v110
	v_add_f32_e32 v111, 1.0, v111
	v_add_f32_e32 v114, 1.0, v114
	v_add_f32_e32 v115, 1.0, v115
	v_rcp_f32_e32 v106, v106
	v_rcp_f32_e32 v107, v107
	v_rcp_f32_e32 v108, v108
	v_rcp_f32_e32 v109, v109
	v_rcp_f32_e32 v110, v110
	v_rcp_f32_e32 v111, v111
	v_rcp_f32_e32 v114, v114
	v_rcp_f32_e32 v115, v115
	s_mov_b64 s[28:29], 0

.LBB0_197:
	v_cvt_pk_bf16_f32 v99, v98, v99
	v_cvt_pk_bf16_f32 v98, v96, v97
	v_cvt_pk_bf16_f32 v96, v100, v101
	v_cvt_pk_bf16_f32 v97, v102, v103
	s_branch .Lp1pl_12

.Lp1pl_12:
	global_store_dwordx4 v202, v[96:99], s[94:95] offset:256 nt
	s_cmp_gt_i32 s13, 2
	s_mov_b64 s[28:29], -1
	s_cbranch_scc0 .LBB0_200
	v_mul_f32_e32 v96, 0xbfb8aa3b, v92
	v_exp_f32_e32 v96, v96
	v_mul_f32_e32 v97, 0xbfb8aa3b, v93
	v_exp_f32_e32 v97, v97
	v_mul_f32_e32 v99, 0xbfb8aa3b, v95
	v_add_f32_e32 v96, 1.0, v96
	v_rcp_f32_e32 v98, v96
	v_mul_f32_e32 v96, 0xbfb8aa3b, v94
	v_exp_f32_e32 v96, v96
	v_exp_f32_e32 v101, v99
	v_add_f32_e32 v97, 1.0, v97
	v_rcp_f32_e32 v99, v97
	v_add_f32_e32 v96, 1.0, v96
	v_mul_f32_e32 v97, 0xbfb8aa3b, v88
	v_rcp_f32_e32 v100, v96
	v_add_f32_e32 v96, 1.0, v101
	v_exp_f32_e32 v97, v97
	v_mul_f32_e32 v101, 0xbfb8aa3b, v89
	v_exp_f32_e32 v103, v101
	v_rcp_f32_e32 v101, v96
	v_add_f32_e32 v96, 1.0, v97
	v_mul_f32_e32 v97, 0xbfb8aa3b, v90
	v_rcp_f32_e32 v102, v96
	v_add_f32_e32 v96, 1.0, v103
	v_exp_f32_e32 v97, v97
	v_mul_f32_e32 v103, 0xbfb8aa3b, v91
	v_exp_f32_e32 v105, v103
	v_rcp_f32_e32 v103, v96
	v_add_f32_e32 v96, 1.0, v97
	v_rcp_f32_e32 v104, v96
	v_add_f32_e32 v96, 1.0, v105
	v_rcp_f32_e32 v105, v96
	s_mov_b64 s[28:29], 0

.LBB0_203:
	v_cvt_pk_bf16_f32 v203, v90, v91
	v_cvt_pk_bf16_f32 v90, v92, v93
	v_cvt_pk_bf16_f32 v91, v94, v95
	v_cvt_pk_bf16_f32 v92, v88, v89
	v_mov_b32_e32 v93, v203
	s_branch .Lp1pl_11
.LBB0_204:
	v_cvt_pk_bf16_f32 v90, v98, v99
	v_cvt_pk_bf16_f32 v91, v100, v101
	v_cvt_pk_bf16_f32 v92, v102, v103
	v_cvt_pk_bf16_f32 v93, v104, v105
.Lp1pl_11:
	s_mul_i32 s94, s26, 0x40
	s_add_u32 s94, s96, s94
	s_addc_u32 s95, s97, 0
	s_cmp_gt_i32 s13, 2
	s_mov_b64 s[28:29], -1
	global_store_dwordx4 v202, v[90:93], s[94:95] nt
	s_cbranch_scc0 .LBB0_206
	s_nop 0
	v_mul_f32_e32 v90, 0xbfb8aa3b, v84
	v_mul_f32_e32 v91, 0xbfb8aa3b, v85
	v_mul_f32_e32 v92, 0xbfb8aa3b, v86
	v_mul_f32_e32 v93, 0xbfb8aa3b, v87
	v_mul_f32_e32 v94, 0xbfb8aa3b, v80
	v_mul_f32_e32 v95, 0xbfb8aa3b, v81
	v_mul_f32_e32 v98, 0xbfb8aa3b, v82
	v_mul_f32_e32 v99, 0xbfb8aa3b, v83
	v_exp_f32_e32 v90, v90
	v_exp_f32_e32 v91, v91
	v_exp_f32_e32 v92, v92
	v_exp_f32_e32 v93, v93
	v_exp_f32_e32 v94, v94
	v_exp_f32_e32 v95, v95
	v_exp_f32_e32 v98, v98
	v_exp_f32_e32 v99, v99
	v_add_f32_e32 v90, 1.0, v90
	v_add_f32_e32 v91, 1.0, v91
	v_add_f32_e32 v92, 1.0, v92
	v_add_f32_e32 v93, 1.0, v93
	v_add_f32_e32 v94, 1.0, v94
	v_add_f32_e32 v95, 1.0, v95
	v_add_f32_e32 v98, 1.0, v98
	v_add_f32_e32 v99, 1.0, v99
	v_rcp_f32_e32 v90, v90
	v_rcp_f32_e32 v91, v91
	v_rcp_f32_e32 v92, v92
	v_rcp_f32_e32 v93, v93
	v_rcp_f32_e32 v94, v94
	v_rcp_f32_e32 v95, v95
	v_rcp_f32_e32 v98, v98
	v_rcp_f32_e32 v99, v99
	s_mov_b64 s[28:29], 0

.LBB0_209:
	v_cvt_pk_bf16_f32 v83, v82, v83
	v_cvt_pk_bf16_f32 v82, v80, v81
	v_cvt_pk_bf16_f32 v80, v84, v85
	v_cvt_pk_bf16_f32 v81, v86, v87
	s_branch .Lp1pl_10

.Lp1pl_10:
	global_store_dwordx4 v202, v[80:83], s[94:95] offset:256 nt
	s_cmp_gt_i32 s13, 2
	s_mov_b64 s[28:29], -1
	s_cbranch_scc0 .LBB0_212
	v_mul_f32_e32 v80, 0xbfb8aa3b, v76
	v_exp_f32_e32 v80, v80
	v_mul_f32_e32 v81, 0xbfb8aa3b, v77
	v_exp_f32_e32 v81, v81
	v_mul_f32_e32 v83, 0xbfb8aa3b, v79
	v_add_f32_e32 v80, 1.0, v80
	v_rcp_f32_e32 v82, v80
	v_mul_f32_e32 v80, 0xbfb8aa3b, v78
	v_exp_f32_e32 v80, v80
	v_exp_f32_e32 v85, v83
	v_add_f32_e32 v81, 1.0, v81
	v_rcp_f32_e32 v83, v81
	v_add_f32_e32 v80, 1.0, v80
	v_mul_f32_e32 v81, 0xbfb8aa3b, v72
	v_rcp_f32_e32 v84, v80
	v_add_f32_e32 v80, 1.0, v85
	v_exp_f32_e32 v81, v81
	v_mul_f32_e32 v85, 0xbfb8aa3b, v73
	v_exp_f32_e32 v87, v85
	v_rcp_f32_e32 v85, v80
	v_add_f32_e32 v80, 1.0, v81
	v_mul_f32_e32 v81, 0xbfb8aa3b, v74
	v_rcp_f32_e32 v86, v80
	v_add_f32_e32 v80, 1.0, v87
	v_exp_f32_e32 v81, v81
	v_mul_f32_e32 v87, 0xbfb8aa3b, v75
	v_exp_f32_e32 v89, v87
	v_rcp_f32_e32 v87, v80
	v_add_f32_e32 v80, 1.0, v81
	v_rcp_f32_e32 v88, v80
	v_add_f32_e32 v80, 1.0, v89
	v_rcp_f32_e32 v89, v80
	s_mov_b64 s[28:29], 0

.LBB0_215:
	v_cvt_pk_bf16_f32 v203, v74, v75
	v_cvt_pk_bf16_f32 v74, v76, v77
	v_cvt_pk_bf16_f32 v75, v78, v79
	v_cvt_pk_bf16_f32 v76, v72, v73
	v_mov_b32_e32 v77, v203
	s_branch .Lp1pl_9
.LBB0_216:
	v_cvt_pk_bf16_f32 v74, v82, v83
	v_cvt_pk_bf16_f32 v75, v84, v85
	v_cvt_pk_bf16_f32 v76, v86, v87
	v_cvt_pk_bf16_f32 v77, v88, v89
.Lp1pl_9:
	s_mul_i32 s94, s26, 0x60
	s_add_u32 s94, s96, s94
	s_addc_u32 s95, s97, 0
	s_cmp_gt_i32 s13, 2
	s_mov_b64 s[28:29], -1
	global_store_dwordx4 v202, v[74:77], s[94:95] nt
	s_cbranch_scc0 .LBB0_218
	s_nop 0
	v_mul_f32_e32 v74, 0xbfb8aa3b, v68
	v_mul_f32_e32 v75, 0xbfb8aa3b, v69
	v_mul_f32_e32 v76, 0xbfb8aa3b, v70
	v_mul_f32_e32 v77, 0xbfb8aa3b, v71
	v_mul_f32_e32 v78, 0xbfb8aa3b, v64
	v_mul_f32_e32 v79, 0xbfb8aa3b, v65
	v_mul_f32_e32 v82, 0xbfb8aa3b, v66
	v_mul_f32_e32 v83, 0xbfb8aa3b, v67
	v_exp_f32_e32 v74, v74
	v_exp_f32_e32 v75, v75
	v_exp_f32_e32 v76, v76
	v_exp_f32_e32 v77, v77
	v_exp_f32_e32 v78, v78
	v_exp_f32_e32 v79, v79
	v_exp_f32_e32 v82, v82
	v_exp_f32_e32 v83, v83
	v_add_f32_e32 v74, 1.0, v74
	v_add_f32_e32 v75, 1.0, v75
	v_add_f32_e32 v76, 1.0, v76
	v_add_f32_e32 v77, 1.0, v77
	v_add_f32_e32 v78, 1.0, v78
	v_add_f32_e32 v79, 1.0, v79
	v_add_f32_e32 v82, 1.0, v82
	v_add_f32_e32 v83, 1.0, v83
	v_rcp_f32_e32 v74, v74
	v_rcp_f32_e32 v75, v75
	v_rcp_f32_e32 v76, v76
	v_rcp_f32_e32 v77, v77
	v_rcp_f32_e32 v78, v78
	v_rcp_f32_e32 v79, v79
	v_rcp_f32_e32 v82, v82
	v_rcp_f32_e32 v83, v83
	s_mov_b64 s[28:29], 0

.LBB0_221:
	v_cvt_pk_bf16_f32 v67, v66, v67
	v_cvt_pk_bf16_f32 v66, v64, v65
	v_cvt_pk_bf16_f32 v64, v68, v69
	v_cvt_pk_bf16_f32 v65, v70, v71
	s_branch .Lp1pl_8

.Lp1pl_8:
	global_store_dwordx4 v202, v[64:67], s[94:95] offset:256 nt
	s_cmp_gt_i32 s13, 2
	s_mov_b64 s[28:29], -1
	s_cbranch_scc0 .LBB0_224
	v_mul_f32_e32 v64, 0xbfb8aa3b, v60
	v_exp_f32_e32 v64, v64
	v_mul_f32_e32 v65, 0xbfb8aa3b, v61
	v_exp_f32_e32 v65, v65
	v_mul_f32_e32 v67, 0xbfb8aa3b, v63
	v_add_f32_e32 v64, 1.0, v64
	v_rcp_f32_e32 v66, v64
	v_mul_f32_e32 v64, 0xbfb8aa3b, v62
	v_exp_f32_e32 v64, v64
	v_exp_f32_e32 v69, v67
	v_add_f32_e32 v65, 1.0, v65
	v_rcp_f32_e32 v67, v65
	v_add_f32_e32 v64, 1.0, v64
	v_mul_f32_e32 v65, 0xbfb8aa3b, v56
	v_rcp_f32_e32 v68, v64
	v_add_f32_e32 v64, 1.0, v69
	v_exp_f32_e32 v65, v65
	v_mul_f32_e32 v69, 0xbfb8aa3b, v57
	v_exp_f32_e32 v71, v69
	v_rcp_f32_e32 v69, v64
	v_add_f32_e32 v64, 1.0, v65
	v_mul_f32_e32 v65, 0xbfb8aa3b, v58
	v_rcp_f32_e32 v70, v64
	v_add_f32_e32 v64, 1.0, v71
	v_exp_f32_e32 v65, v65
	v_mul_f32_e32 v71, 0xbfb8aa3b, v59
	v_exp_f32_e32 v73, v71
	v_rcp_f32_e32 v71, v64
	v_add_f32_e32 v64, 1.0, v65
	v_rcp_f32_e32 v72, v64
	v_add_f32_e32 v64, 1.0, v73
	v_rcp_f32_e32 v73, v64
	s_mov_b64 s[28:29], 0

.LBB0_227:
	v_cvt_pk_bf16_f32 v203, v58, v59
	v_cvt_pk_bf16_f32 v58, v60, v61
	v_cvt_pk_bf16_f32 v59, v62, v63
	v_cvt_pk_bf16_f32 v60, v56, v57
	v_mov_b32_e32 v61, v203
	s_branch .Lp1pl_7
.LBB0_228:
	v_cvt_pk_bf16_f32 v58, v66, v67
	v_cvt_pk_bf16_f32 v59, v68, v69
	v_cvt_pk_bf16_f32 v60, v70, v71
	v_cvt_pk_bf16_f32 v61, v72, v73
.Lp1pl_7:
	s_mul_i32 s94, s26, 0x100
	s_add_u32 s94, s96, s94
	s_addc_u32 s95, s97, 0
	s_cmp_gt_i32 s13, 2
	s_mov_b64 s[28:29], -1
	global_store_dwordx4 v202, v[58:61], s[94:95] nt
	s_cbranch_scc0 .LBB0_230
	s_nop 0
	v_mul_f32_e32 v58, 0xbfb8aa3b, v52
	v_mul_f32_e32 v59, 0xbfb8aa3b, v53
	v_mul_f32_e32 v60, 0xbfb8aa3b, v54
	v_mul_f32_e32 v61, 0xbfb8aa3b, v55
	v_mul_f32_e32 v62, 0xbfb8aa3b, v48
	v_mul_f32_e32 v63, 0xbfb8aa3b, v49
	v_mul_f32_e32 v66, 0xbfb8aa3b, v50
	v_mul_f32_e32 v67, 0xbfb8aa3b, v51
	v_exp_f32_e32 v58, v58
	v_exp_f32_e32 v59, v59
	v_exp_f32_e32 v60, v60
	v_exp_f32_e32 v61, v61
	v_exp_f32_e32 v62, v62
	v_exp_f32_e32 v63, v63
	v_exp_f32_e32 v66, v66
	v_exp_f32_e32 v67, v67
	v_add_f32_e32 v58, 1.0, v58
	v_add_f32_e32 v59, 1.0, v59
	v_add_f32_e32 v60, 1.0, v60
	v_add_f32_e32 v61, 1.0, v61
	v_add_f32_e32 v62, 1.0, v62
	v_add_f32_e32 v63, 1.0, v63
	v_add_f32_e32 v66, 1.0, v66
	v_add_f32_e32 v67, 1.0, v67
	v_rcp_f32_e32 v58, v58
	v_rcp_f32_e32 v59, v59
	v_rcp_f32_e32 v60, v60
	v_rcp_f32_e32 v61, v61
	v_rcp_f32_e32 v62, v62
	v_rcp_f32_e32 v63, v63
	v_rcp_f32_e32 v66, v66
	v_rcp_f32_e32 v67, v67
	s_mov_b64 s[28:29], 0

.LBB0_233:
	v_cvt_pk_bf16_f32 v51, v50, v51
	v_cvt_pk_bf16_f32 v50, v48, v49
	v_cvt_pk_bf16_f32 v48, v52, v53
	v_cvt_pk_bf16_f32 v49, v54, v55
	s_branch .Lp1pl_6

.Lp1pl_6:
	global_store_dwordx4 v202, v[48:51], s[94:95] offset:256 nt
	s_cmp_gt_i32 s13, 2
	s_mov_b64 s[28:29], -1
	s_cbranch_scc0 .LBB0_236
	v_mul_f32_e32 v48, 0xbfb8aa3b, v44
	v_exp_f32_e32 v48, v48
	v_mul_f32_e32 v49, 0xbfb8aa3b, v45
	v_exp_f32_e32 v49, v49
	v_mul_f32_e32 v51, 0xbfb8aa3b, v47
	v_add_f32_e32 v48, 1.0, v48
	v_rcp_f32_e32 v50, v48
	v_mul_f32_e32 v48, 0xbfb8aa3b, v46
	v_exp_f32_e32 v48, v48
	v_exp_f32_e32 v53, v51
	v_add_f32_e32 v49, 1.0, v49
	v_rcp_f32_e32 v51, v49
	v_add_f32_e32 v48, 1.0, v48
	v_mul_f32_e32 v49, 0xbfb8aa3b, v40
	v_rcp_f32_e32 v52, v48
	v_add_f32_e32 v48, 1.0, v53
	v_exp_f32_e32 v49, v49
	v_mul_f32_e32 v53, 0xbfb8aa3b, v41
	v_exp_f32_e32 v55, v53
	v_rcp_f32_e32 v53, v48
	v_add_f32_e32 v48, 1.0, v49
	v_mul_f32_e32 v49, 0xbfb8aa3b, v42
	v_rcp_f32_e32 v54, v48
	v_add_f32_e32 v48, 1.0, v55
	v_exp_f32_e32 v49, v49
	v_mul_f32_e32 v55, 0xbfb8aa3b, v43
	v_exp_f32_e32 v57, v55
	v_rcp_f32_e32 v55, v48
	v_add_f32_e32 v48, 1.0, v49
	v_rcp_f32_e32 v56, v48
	v_add_f32_e32 v48, 1.0, v57
	v_rcp_f32_e32 v57, v48
	s_mov_b64 s[28:29], 0

.LBB0_239:
	v_cvt_pk_bf16_f32 v203, v42, v43
	v_cvt_pk_bf16_f32 v42, v44, v45
	v_cvt_pk_bf16_f32 v43, v46, v47
	v_cvt_pk_bf16_f32 v44, v40, v41
	v_mov_b32_e32 v45, v203
	s_branch .Lp1pl_5
.LBB0_240:
	v_cvt_pk_bf16_f32 v42, v50, v51
	v_cvt_pk_bf16_f32 v43, v52, v53
	v_cvt_pk_bf16_f32 v44, v54, v55
	v_cvt_pk_bf16_f32 v45, v56, v57
.Lp1pl_5:
	s_mul_i32 s94, s26, 0x120
	s_add_u32 s94, s96, s94
	s_addc_u32 s95, s97, 0
	s_cmp_gt_i32 s13, 2
	s_mov_b64 s[28:29], -1
	global_store_dwordx4 v202, v[42:45], s[94:95] nt
	s_cbranch_scc0 .LBB0_242
	s_nop 0
	v_mul_f32_e32 v42, 0xbfb8aa3b, v36
	v_mul_f32_e32 v43, 0xbfb8aa3b, v37
	v_mul_f32_e32 v44, 0xbfb8aa3b, v38
	v_mul_f32_e32 v45, 0xbfb8aa3b, v39
	v_mul_f32_e32 v46, 0xbfb8aa3b, v32
	v_mul_f32_e32 v47, 0xbfb8aa3b, v33
	v_mul_f32_e32 v50, 0xbfb8aa3b, v34
	v_mul_f32_e32 v51, 0xbfb8aa3b, v35
	v_exp_f32_e32 v42, v42
	v_exp_f32_e32 v43, v43
	v_exp_f32_e32 v44, v44
	v_exp_f32_e32 v45, v45
	v_exp_f32_e32 v46, v46
	v_exp_f32_e32 v47, v47
	v_exp_f32_e32 v50, v50
	v_exp_f32_e32 v51, v51
	v_add_f32_e32 v42, 1.0, v42
	v_add_f32_e32 v43, 1.0, v43
	v_add_f32_e32 v44, 1.0, v44
	v_add_f32_e32 v45, 1.0, v45
	v_add_f32_e32 v46, 1.0, v46
	v_add_f32_e32 v47, 1.0, v47
	v_add_f32_e32 v50, 1.0, v50
	v_add_f32_e32 v51, 1.0, v51
	v_rcp_f32_e32 v42, v42
	v_rcp_f32_e32 v43, v43
	v_rcp_f32_e32 v44, v44
	v_rcp_f32_e32 v45, v45
	v_rcp_f32_e32 v46, v46
	v_rcp_f32_e32 v47, v47
	v_rcp_f32_e32 v50, v50
	v_rcp_f32_e32 v51, v51
	s_mov_b64 s[28:29], 0

.LBB0_245:
	v_cvt_pk_bf16_f32 v35, v34, v35
	v_cvt_pk_bf16_f32 v34, v32, v33
	v_cvt_pk_bf16_f32 v32, v36, v37
	v_cvt_pk_bf16_f32 v33, v38, v39
	s_branch .Lp1pl_4

.Lp1pl_4:
	global_store_dwordx4 v202, v[32:35], s[94:95] offset:256 nt
	s_cmp_gt_i32 s13, 2
	s_mov_b64 s[28:29], -1
	s_cbranch_scc0 .LBB0_248
	v_mul_f32_e32 v32, 0xbfb8aa3b, v28
	v_exp_f32_e32 v32, v32
	v_mul_f32_e32 v33, 0xbfb8aa3b, v29
	v_exp_f32_e32 v33, v33
	v_mul_f32_e32 v35, 0xbfb8aa3b, v31
	v_add_f32_e32 v32, 1.0, v32
	v_rcp_f32_e32 v34, v32
	v_mul_f32_e32 v32, 0xbfb8aa3b, v30
	v_exp_f32_e32 v32, v32
	v_exp_f32_e32 v37, v35
	v_add_f32_e32 v33, 1.0, v33
	v_rcp_f32_e32 v35, v33
	v_add_f32_e32 v32, 1.0, v32
	v_mul_f32_e32 v33, 0xbfb8aa3b, v24
	v_rcp_f32_e32 v36, v32
	v_add_f32_e32 v32, 1.0, v37
	v_exp_f32_e32 v33, v33
	v_mul_f32_e32 v37, 0xbfb8aa3b, v25
	v_exp_f32_e32 v39, v37
	v_rcp_f32_e32 v37, v32
	v_add_f32_e32 v32, 1.0, v33
	v_mul_f32_e32 v33, 0xbfb8aa3b, v26
	v_rcp_f32_e32 v38, v32
	v_add_f32_e32 v32, 1.0, v39
	v_exp_f32_e32 v33, v33
	v_mul_f32_e32 v39, 0xbfb8aa3b, v27
	v_exp_f32_e32 v41, v39
	v_rcp_f32_e32 v39, v32
	v_add_f32_e32 v32, 1.0, v33
	v_rcp_f32_e32 v40, v32
	v_add_f32_e32 v32, 1.0, v41
	v_rcp_f32_e32 v41, v32
	s_mov_b64 s[28:29], 0

.LBB0_251:
	v_cvt_pk_bf16_f32 v203, v26, v27
	v_cvt_pk_bf16_f32 v26, v28, v29
	v_cvt_pk_bf16_f32 v27, v30, v31
	v_cvt_pk_bf16_f32 v28, v24, v25
	v_mov_b32_e32 v29, v203
	s_branch .Lp1pl_3
.LBB0_252:
	v_cvt_pk_bf16_f32 v26, v34, v35
	v_cvt_pk_bf16_f32 v27, v36, v37
	v_cvt_pk_bf16_f32 v28, v38, v39
	v_cvt_pk_bf16_f32 v29, v40, v41
.Lp1pl_3:
	s_mul_i32 s94, s26, 0x140
	s_add_u32 s94, s96, s94
	s_addc_u32 s95, s97, 0
	s_cmp_gt_i32 s13, 2
	s_mov_b64 s[28:29], -1
	global_store_dwordx4 v202, v[26:29], s[94:95] nt
	s_cbranch_scc0 .LBB0_254
	s_nop 0
	v_mul_f32_e32 v26, 0xbfb8aa3b, v20
	v_mul_f32_e32 v27, 0xbfb8aa3b, v21
	v_mul_f32_e32 v28, 0xbfb8aa3b, v22
	v_mul_f32_e32 v29, 0xbfb8aa3b, v23
	v_mul_f32_e32 v30, 0xbfb8aa3b, v16
	v_mul_f32_e32 v31, 0xbfb8aa3b, v17
	v_mul_f32_e32 v34, 0xbfb8aa3b, v18
	v_mul_f32_e32 v35, 0xbfb8aa3b, v19
	v_exp_f32_e32 v26, v26
	v_exp_f32_e32 v27, v27
	v_exp_f32_e32 v28, v28
	v_exp_f32_e32 v29, v29
	v_exp_f32_e32 v30, v30
	v_exp_f32_e32 v31, v31
	v_exp_f32_e32 v34, v34
	v_exp_f32_e32 v35, v35
	v_add_f32_e32 v26, 1.0, v26
	v_add_f32_e32 v27, 1.0, v27
	v_add_f32_e32 v28, 1.0, v28
	v_add_f32_e32 v29, 1.0, v29
	v_add_f32_e32 v30, 1.0, v30
	v_add_f32_e32 v31, 1.0, v31
	v_add_f32_e32 v34, 1.0, v34
	v_add_f32_e32 v35, 1.0, v35
	v_rcp_f32_e32 v26, v26
	v_rcp_f32_e32 v27, v27
	v_rcp_f32_e32 v28, v28
	v_rcp_f32_e32 v29, v29
	v_rcp_f32_e32 v30, v30
	v_rcp_f32_e32 v31, v31
	v_rcp_f32_e32 v34, v34
	v_rcp_f32_e32 v35, v35
	s_mov_b64 s[28:29], 0

.LBB0_257:
	v_cvt_pk_bf16_f32 v19, v18, v19
	v_cvt_pk_bf16_f32 v18, v16, v17
	v_cvt_pk_bf16_f32 v16, v20, v21
	v_cvt_pk_bf16_f32 v17, v22, v23
	s_branch .Lp1pl_2

.Lp1pl_2:
	global_store_dwordx4 v202, v[16:19], s[94:95] offset:256 nt
	s_cmp_gt_i32 s13, 2
	s_mov_b64 s[28:29], -1
	s_cbranch_scc0 .LBB0_260
	v_mul_f32_e32 v16, 0xbfb8aa3b, v12
	v_exp_f32_e32 v16, v16
	v_mul_f32_e32 v17, 0xbfb8aa3b, v13
	v_exp_f32_e32 v17, v17
	v_mul_f32_e32 v19, 0xbfb8aa3b, v15
	v_add_f32_e32 v16, 1.0, v16
	v_rcp_f32_e32 v18, v16
	v_mul_f32_e32 v16, 0xbfb8aa3b, v14
	v_exp_f32_e32 v16, v16
	v_exp_f32_e32 v21, v19
	v_add_f32_e32 v17, 1.0, v17
	v_rcp_f32_e32 v19, v17
	v_add_f32_e32 v16, 1.0, v16
	v_mul_f32_e32 v17, 0xbfb8aa3b, v8
	v_rcp_f32_e32 v20, v16
	v_add_f32_e32 v16, 1.0, v21
	v_exp_f32_e32 v17, v17
	v_mul_f32_e32 v21, 0xbfb8aa3b, v9
	v_exp_f32_e32 v23, v21
	v_rcp_f32_e32 v21, v16
	v_add_f32_e32 v16, 1.0, v17
	v_mul_f32_e32 v17, 0xbfb8aa3b, v10
	v_rcp_f32_e32 v22, v16
	v_add_f32_e32 v16, 1.0, v23
	v_exp_f32_e32 v17, v17
	v_mul_f32_e32 v23, 0xbfb8aa3b, v11
	v_exp_f32_e32 v25, v23
	v_rcp_f32_e32 v23, v16
	v_add_f32_e32 v16, 1.0, v17
	v_rcp_f32_e32 v24, v16
	v_add_f32_e32 v16, 1.0, v25
	v_rcp_f32_e32 v25, v16
	s_mov_b64 s[28:29], 0

.LBB0_263:
	v_cvt_pk_bf16_f32 v203, v10, v11
	v_cvt_pk_bf16_f32 v10, v12, v13
	v_cvt_pk_bf16_f32 v11, v14, v15
	v_cvt_pk_bf16_f32 v12, v8, v9
	v_mov_b32_e32 v13, v203
	s_branch .Lp1pl_1
.LBB0_264:
	v_cvt_pk_bf16_f32 v10, v18, v19
	v_cvt_pk_bf16_f32 v11, v20, v21
	v_cvt_pk_bf16_f32 v12, v22, v23
	v_cvt_pk_bf16_f32 v13, v24, v25
.Lp1pl_1:
	s_mul_i32 s94, s26, 0x160
	s_add_u32 s94, s96, s94
	s_addc_u32 s95, s97, 0
	s_cmp_gt_i32 s13, 2
	s_mov_b64 s[24:25], -1
	global_store_dwordx4 v202, v[10:13], s[94:95] nt
	s_cbranch_scc0 .LBB0_266
	s_nop 0
	v_mul_f32_e32 v10, 0xbfb8aa3b, v4
	v_mul_f32_e32 v11, 0xbfb8aa3b, v5
	v_mul_f32_e32 v12, 0xbfb8aa3b, v6
	v_mul_f32_e32 v13, 0xbfb8aa3b, v7
	v_mul_f32_e32 v14, 0xbfb8aa3b, v0
	v_mul_f32_e32 v15, 0xbfb8aa3b, v1
	v_mul_f32_e32 v18, 0xbfb8aa3b, v2
	v_mul_f32_e32 v19, 0xbfb8aa3b, v3
	v_exp_f32_e32 v10, v10
	v_exp_f32_e32 v11, v11
	v_exp_f32_e32 v12, v12
	v_exp_f32_e32 v13, v13
	v_exp_f32_e32 v14, v14
	v_exp_f32_e32 v15, v15
	v_exp_f32_e32 v18, v18
	v_exp_f32_e32 v19, v19
	v_add_f32_e32 v10, 1.0, v10
	v_add_f32_e32 v11, 1.0, v11
	v_add_f32_e32 v12, 1.0, v12
	v_add_f32_e32 v13, 1.0, v13
	v_add_f32_e32 v14, 1.0, v14
	v_add_f32_e32 v15, 1.0, v15
	v_add_f32_e32 v18, 1.0, v18
	v_add_f32_e32 v19, 1.0, v19
	v_rcp_f32_e32 v10, v10
	v_rcp_f32_e32 v11, v11
	v_rcp_f32_e32 v12, v12
	v_rcp_f32_e32 v13, v13
	v_rcp_f32_e32 v14, v14
	v_rcp_f32_e32 v15, v15
	v_rcp_f32_e32 v18, v18
	v_rcp_f32_e32 v19, v19
	s_mov_b64 s[24:25], 0

.LBB0_269:
	v_cvt_pk_bf16_f32 v3, v2, v3
	v_cvt_pk_bf16_f32 v2, v0, v1
	v_cvt_pk_bf16_f32 v0, v4, v5
	v_cvt_pk_bf16_f32 v1, v6, v7
	s_branch .Lp1pl_0

.Lp1pl_0:
	global_store_dwordx4 v202, v[0:3], s[94:95] offset:256 nt
	s_andn2_b64 vcc, exec, s[16:17]
	s_mov_b64 s[16:17], -1
	s_cbranch_vccnz .LBB0_146
	s_andn2_b64 vcc, exec, s[6:7]
	s_cbranch_vccnz .LBB0_145
	s_barrier
	s_branch .LBB0_145
